# strategy 4: 4-phase GEMM loops without per-segment flips + one static s_setprio 1 for waves 4-7 during GEMM phases
# speedup vs baseline: 1.0120x; 1.0120x over previous
; __global__ void __launch_bounds__(512, 2) mega(Params p_arg, int ph_lo, int ph_hi) {
;     ...
;     for (int ph = ph_lo; ph < ph_hi; ++ph) {
;         KParams p = (KParams)__builtin_amdgcn_kernarg_segment_ptr();
;         asm volatile("" : "+s"(p));
;         run_phase(p, ph, lds);
;         if (DUP_MASK) { const int s = (ph - 1) % NPL; if (ph >= 1 && ph < NPHASE - 1 && ((DUP_MASK >> s) & 1)) { __syncthreads(); run_phase(p, ph, lds); } }
;         if (ph + 1 < ph_hi) {
;             if (ph_hi > NPHASE) { __threadfence(); cg::this_grid().sync(); }
;             else xcd_barrier(xb);
;         }
;     }
.LBB0_15:
	s_setprio 0
	s_add_i32 s6, s6, 1
	s_cmp_ge_i32 s6, s7
	s_mov_b64 s[0:1], -1
	s_cbranch_scc1 .LBB0_10
	s_branch .LBB0_449

; #define LAS __attribute__((address_space(3)))
; __device__ __forceinline__ void run_phase(KParams p, int ph, LAS unsigned char* lds) {
;     if (ph == 0) { prepass(p, lds); return; }
;     if (ph == NPHASE - 1) { final_norm_phase(p); return; }
;     const int l = (ph - 1) / NPL, s = (ph - 1) % NPL;
;     const int Mx = (l == 0) ? MT : ML;
;     const bf16_t* wt = p->wt + (size_t)l * WT_LAYER;
;     const float* modl = p->mod + (size_t)l * 9 * 12288;
;     switch (s) {
.LBB0_22:
	s_add_i32 s8, s6, -1
	s_ashr_i32 s9, s8, 31
	s_lshr_b32 s9, s9, 29
	s_add_i32 s9, s8, s9
	s_ashr_i32 s12, s9, 3
	s_and_b32 s9, s9, -8
	s_sub_i32 s98, s8, s9
	s_mov_b32 s101, 0
	s_cmp_eq_u32 s98, 1
	s_cselect_b32 s101, 1, s101
	s_cmp_eq_u32 s98, 6
	s_cselect_b32 s101, 1, s101
	s_cmp_eq_u32 s98, 4
	s_cselect_b32 s101, 1, s101
	s_cmp_eq_u32 s98, 7
	s_cselect_b32 s101, 1, s101
	v_readfirstlane_b32 s100, v208
	s_nop 3
	s_lshr_b32 s100, s100, 8
	s_and_b32 s100, s100, s101
	s_cmp_eq_u32 s100, 0
	s_cbranch_scc1 .Lsprio_skip
	s_setprio 1
